# same as previous best plus dtype comment line and truthful metadata sgpr_count (no instruction change)
# baseline (speedup 1.0000x reference)
amdhsa.kernels:
  - .agpr_count:     0
    .args:
      - .offset:         0
        .size:           320
        .value_kind:     by_value
      - .offset:         320
        .size:           4
        .value_kind:     hidden_block_count_x
      - .offset:         324
        .size:           4
        .value_kind:     hidden_block_count_y
      - .offset:         328
        .size:           4
        .value_kind:     hidden_block_count_z
      - .offset:         332
        .size:           2
        .value_kind:     hidden_group_size_x
      - .offset:         334
        .size:           2
        .value_kind:     hidden_group_size_y
      - .offset:         336
        .size:           2
        .value_kind:     hidden_group_size_z
      - .offset:         338
        .size:           2
        .value_kind:     hidden_remainder_x
      - .offset:         340
        .size:           2
        .value_kind:     hidden_remainder_y
      - .offset:         342
        .size:           2
        .value_kind:     hidden_remainder_z
      - .offset:         360
        .size:           8
        .value_kind:     hidden_global_offset_x
      - .offset:         368
        .size:           8
        .value_kind:     hidden_global_offset_y
      - .offset:         376
        .size:           8
        .value_kind:     hidden_global_offset_z
      - .offset:         384
        .size:           2
        .value_kind:     hidden_grid_dims
      - .offset:         408
        .size:           8
        .value_kind:     hidden_multigrid_sync_arg
      - .offset:         440
        .size:           4
        .value_kind:     hidden_dynamic_lds_size
    .group_segment_fixed_size: 0
    .kernarg_segment_align: 8
    .kernarg_segment_size: 576
    .language:       OpenCL C
    .language_version:
      - 2
      - 0
    .max_flat_workgroup_size: 512
    .name:           _Z4mega4Args
    .private_segment_fixed_size: 0
    .sgpr_count:     108
    .sgpr_spill_count: 55
    .symbol:         _Z4mega4Args.kd
    .uniform_work_group_size: 1
    .uses_dynamic_stack: false
    .vgpr_count:     256
    .vgpr_spill_count: 0
    .wavefront_size: 64
